# v145 + attention value waves: no K-tile staging in the last two iterations of a unit (tiles that do not exist), iteration 0 stages tile 1 with one global round trip using idle V-ring registers
# baseline (speedup 1.0000x reference)
.LBB0_397:
	s_add_i32 s8, s30, 1
	s_cmp_ge_i32 s8, s27
	s_cbranch_scc1 .Lav_tailbody
	s_add_i32 s8, s19, 2
	s_mul_hi_u32 s9, s8, 0xaaaaaaab
	s_lshr_b32 s9, s9, 1
	s_mul_i32 s9, s9, 3
	s_sub_i32 s8, s8, s9
	s_mul_i32 s8, s8, 0xa400
	v_add_u32_e32 v145, s8, v170
	s_lshl_b32 s8, s30, 2
	s_add_i32 s8, s8, -4
	s_and_b32 s8, s8, 4
	v_readlane_b32 s9, v255, 28
	s_or_b32 s8, s8, s9
	s_mulk_i32 s8, 0x1080
	s_add_i32 s8, s8, 0x1ec00
	v_add_u32_e32 v0, s8, v168
	ds_read_b32 v0, v0 offset:4096
	s_bfe_u32 s8, s18, 0x10002
	s_mulk_i32 s8, 0x4200
	s_add_i32 s8, s8, 0xfffffc00
	v_add_u32_e32 v2, s8, v172
	s_mul_hi_u32 s8, s19, 0xaaaaaaab
	s_lshr_b32 s8, s8, 1
	s_mul_i32 s8, s8, 0xfffe1400
	s_add_i32 s8, s8, 0xffff5c00
	v_add_u32_e32 v3, s8, v144
	ds_read_b128 v[176:179], v2
	ds_read_b128 v[180:183], v2 offset:1024
	ds_read_b128 v[184:187], v2 offset:2048
	ds_read_b128 v[188:191], v2 offset:3072
	ds_read_b64_tr_b16 v[220:221], v3
	ds_read_b64_tr_b16 v[222:223], v3 offset:5248
	ds_read_b64_tr_b16 v[224:225], v3 offset:64
	ds_read_b64_tr_b16 v[226:227], v3 offset:5312
	ds_read_b64_tr_b16 v[228:229], v3 offset:128
	ds_read_b64_tr_b16 v[230:231], v3 offset:5376
	ds_read_b64_tr_b16 v[232:233], v3 offset:192
	ds_read_b64_tr_b16 v[234:235], v3 offset:5440
	ds_read_b64_tr_b16 v[236:237], v3 offset:256
	ds_read_b64_tr_b16 v[238:239], v3 offset:5504
	s_waitcnt lgkmcnt(14)
	v_cmp_neq_f32_e32 vcc, 1.0, v0
	s_cbranch_vccz .Lav_noscale
	v_pk_mul_f32 v[142:143], v[0:1], v[142:143] op_sel_hi:[0,1]
	v_pk_mul_f32 v[140:141], v[0:1], v[140:141] op_sel_hi:[0,1]
	v_pk_mul_f32 v[138:139], v[0:1], v[138:139] op_sel_hi:[0,1]
	v_pk_mul_f32 v[136:137], v[0:1], v[136:137] op_sel_hi:[0,1]
	v_pk_mul_f32 v[134:135], v[0:1], v[134:135] op_sel_hi:[0,1]
	v_pk_mul_f32 v[132:133], v[0:1], v[132:133] op_sel_hi:[0,1]
	v_pk_mul_f32 v[130:131], v[0:1], v[130:131] op_sel_hi:[0,1]
	v_pk_mul_f32 v[128:129], v[0:1], v[128:129] op_sel_hi:[0,1]
	v_pk_mul_f32 v[126:127], v[0:1], v[126:127] op_sel_hi:[0,1]
	v_pk_mul_f32 v[124:125], v[0:1], v[124:125] op_sel_hi:[0,1]
	v_pk_mul_f32 v[122:123], v[0:1], v[122:123] op_sel_hi:[0,1]
	v_pk_mul_f32 v[120:121], v[0:1], v[120:121] op_sel_hi:[0,1]
	v_pk_mul_f32 v[118:119], v[0:1], v[118:119] op_sel_hi:[0,1]
	v_pk_mul_f32 v[116:117], v[0:1], v[116:117] op_sel_hi:[0,1]
	v_pk_mul_f32 v[114:115], v[0:1], v[114:115] op_sel_hi:[0,1]
	v_pk_mul_f32 v[112:113], v[0:1], v[112:113] op_sel_hi:[0,1]
	v_pk_mul_f32 v[110:111], v[0:1], v[110:111] op_sel_hi:[0,1]
	v_pk_mul_f32 v[108:109], v[0:1], v[108:109] op_sel_hi:[0,1]
	v_pk_mul_f32 v[106:107], v[0:1], v[106:107] op_sel_hi:[0,1]
	v_pk_mul_f32 v[104:105], v[0:1], v[104:105] op_sel_hi:[0,1]
	v_pk_mul_f32 v[102:103], v[0:1], v[102:103] op_sel_hi:[0,1]
	v_pk_mul_f32 v[100:101], v[0:1], v[100:101] op_sel_hi:[0,1]
	v_pk_mul_f32 v[98:99], v[0:1], v[98:99] op_sel_hi:[0,1]
	v_pk_mul_f32 v[96:97], v[0:1], v[96:97] op_sel_hi:[0,1]
	v_pk_mul_f32 v[94:95], v[0:1], v[94:95] op_sel_hi:[0,1]
	v_pk_mul_f32 v[92:93], v[0:1], v[92:93] op_sel_hi:[0,1]
	v_pk_mul_f32 v[90:91], v[0:1], v[90:91] op_sel_hi:[0,1]
	v_pk_mul_f32 v[88:89], v[0:1], v[88:89] op_sel_hi:[0,1]
	v_pk_mul_f32 v[86:87], v[0:1], v[86:87] op_sel_hi:[0,1]
	v_pk_mul_f32 v[84:85], v[0:1], v[84:85] op_sel_hi:[0,1]
	v_pk_mul_f32 v[82:83], v[0:1], v[82:83] op_sel_hi:[0,1]
	v_pk_mul_f32 v[80:81], v[0:1], v[80:81] op_sel_hi:[0,1]
	v_pk_mul_f32 v[78:79], v[0:1], v[78:79] op_sel_hi:[0,1]
	v_pk_mul_f32 v[76:77], v[0:1], v[76:77] op_sel_hi:[0,1]
	v_pk_mul_f32 v[74:75], v[0:1], v[74:75] op_sel_hi:[0,1]
	v_pk_mul_f32 v[72:73], v[0:1], v[72:73] op_sel_hi:[0,1]
	v_pk_mul_f32 v[70:71], v[0:1], v[70:71] op_sel_hi:[0,1]
	v_pk_mul_f32 v[68:69], v[0:1], v[68:69] op_sel_hi:[0,1]
	v_pk_mul_f32 v[66:67], v[0:1], v[66:67] op_sel_hi:[0,1]
	v_pk_mul_f32 v[64:65], v[0:1], v[64:65] op_sel_hi:[0,1]
	v_pk_mul_f32 v[62:63], v[0:1], v[62:63] op_sel_hi:[0,1]
	v_pk_mul_f32 v[60:61], v[0:1], v[60:61] op_sel_hi:[0,1]
	v_pk_mul_f32 v[58:59], v[0:1], v[58:59] op_sel_hi:[0,1]
	v_pk_mul_f32 v[56:57], v[0:1], v[56:57] op_sel_hi:[0,1]
	v_pk_mul_f32 v[54:55], v[0:1], v[54:55] op_sel_hi:[0,1]
	v_pk_mul_f32 v[52:53], v[0:1], v[52:53] op_sel_hi:[0,1]
	v_pk_mul_f32 v[50:51], v[0:1], v[50:51] op_sel_hi:[0,1]
	v_pk_mul_f32 v[48:49], v[0:1], v[48:49] op_sel_hi:[0,1]
	v_pk_mul_f32 v[46:47], v[0:1], v[46:47] op_sel_hi:[0,1]
	v_pk_mul_f32 v[44:45], v[0:1], v[44:45] op_sel_hi:[0,1]
	v_pk_mul_f32 v[42:43], v[0:1], v[42:43] op_sel_hi:[0,1]
	v_pk_mul_f32 v[40:41], v[0:1], v[40:41] op_sel_hi:[0,1]
	v_pk_mul_f32 v[38:39], v[0:1], v[38:39] op_sel_hi:[0,1]
	v_pk_mul_f32 v[36:37], v[0:1], v[36:37] op_sel_hi:[0,1]
	v_pk_mul_f32 v[34:35], v[0:1], v[34:35] op_sel_hi:[0,1]
	v_pk_mul_f32 v[32:33], v[0:1], v[32:33] op_sel_hi:[0,1]
	v_pk_mul_f32 v[30:31], v[0:1], v[30:31] op_sel_hi:[0,1]
	v_pk_mul_f32 v[28:29], v[0:1], v[28:29] op_sel_hi:[0,1]
	v_pk_mul_f32 v[26:27], v[0:1], v[26:27] op_sel_hi:[0,1]
	v_pk_mul_f32 v[24:25], v[0:1], v[24:25] op_sel_hi:[0,1]
	v_pk_mul_f32 v[22:23], v[0:1], v[22:23] op_sel_hi:[0,1]
	v_pk_mul_f32 v[20:21], v[0:1], v[20:21] op_sel_hi:[0,1]
	v_pk_mul_f32 v[18:19], v[0:1], v[18:19] op_sel_hi:[0,1]
	v_pk_mul_f32 v[16:17], v[0:1], v[16:17] op_sel_hi:[0,1]
.Lav_noscale:
	ds_read_b64_tr_b16 v[240:241], v3 offset:320
	ds_read_b64_tr_b16 v[242:243], v3 offset:5568
	ds_read_b64_tr_b16 v[244:245], v3 offset:384
	ds_read_b64_tr_b16 v[246:247], v3 offset:5632
	ds_read_b64_tr_b16 v[248:249], v3 offset:448
	ds_read_b64_tr_b16 v[250:251], v3 offset:5696
	s_waitcnt lgkmcnt(14)
	v_mfma_f32_32x32x16_bf16 v[128:143], v[220:223], v[176:179], v[128:143]
	ds_read_b64_tr_b16 v[220:221], v3 offset:10496
	ds_read_b64_tr_b16 v[222:223], v3 offset:15744
	s_waitcnt lgkmcnt(14)
	v_mfma_f32_32x32x16_bf16 v[112:127], v[224:227], v[176:179], v[112:127]
	ds_read_b64_tr_b16 v[224:225], v3 offset:10560
	ds_read_b64_tr_b16 v[226:227], v3 offset:15808
	s_waitcnt lgkmcnt(14)
	v_mfma_f32_32x32x16_bf16 v[96:111], v[228:231], v[176:179], v[96:111]
	ds_read_b64_tr_b16 v[228:229], v3 offset:10624
	ds_read_b64_tr_b16 v[230:231], v3 offset:15872
	s_waitcnt lgkmcnt(14)
	v_mfma_f32_32x32x16_bf16 v[80:95], v[232:235], v[176:179], v[80:95]
	ds_read_b64_tr_b16 v[232:233], v3 offset:10688
	ds_read_b64_tr_b16 v[234:235], v3 offset:15936
	s_waitcnt lgkmcnt(14)
	v_mfma_f32_32x32x16_bf16 v[64:79], v[236:239], v[176:179], v[64:79]
	ds_read_b64_tr_b16 v[236:237], v3 offset:10752
	ds_read_b64_tr_b16 v[238:239], v3 offset:16000
	s_waitcnt lgkmcnt(14)
	v_mfma_f32_32x32x16_bf16 v[48:63], v[240:243], v[176:179], v[48:63]
	ds_read_b64_tr_b16 v[240:241], v3 offset:10816
	ds_read_b64_tr_b16 v[242:243], v3 offset:16064
	s_waitcnt lgkmcnt(14)
	v_mfma_f32_32x32x16_bf16 v[32:47], v[244:247], v[176:179], v[32:47]
	ds_read_b64_tr_b16 v[244:245], v3 offset:10880
	ds_read_b64_tr_b16 v[246:247], v3 offset:16128
	s_waitcnt lgkmcnt(14)
	v_mfma_f32_32x32x16_bf16 v[16:31], v[248:251], v[176:179], v[16:31]
	ds_read_b64_tr_b16 v[248:249], v3 offset:10944
	ds_read_b64_tr_b16 v[250:251], v3 offset:16192
	s_waitcnt lgkmcnt(14)
	v_mfma_f32_32x32x16_bf16 v[128:143], v[220:223], v[180:183], v[128:143]
	ds_read_b64_tr_b16 v[220:221], v3 offset:20992
	ds_read_b64_tr_b16 v[222:223], v3 offset:26240
	s_waitcnt lgkmcnt(14)
	v_mfma_f32_32x32x16_bf16 v[112:127], v[224:227], v[180:183], v[112:127]
	ds_read_b64_tr_b16 v[224:225], v3 offset:21056
	ds_read_b64_tr_b16 v[226:227], v3 offset:26304
	s_waitcnt lgkmcnt(14)
	v_mfma_f32_32x32x16_bf16 v[96:111], v[228:231], v[180:183], v[96:111]
	ds_read_b64_tr_b16 v[228:229], v3 offset:21120
	ds_read_b64_tr_b16 v[230:231], v3 offset:26368
	s_waitcnt lgkmcnt(14)
	v_mfma_f32_32x32x16_bf16 v[80:95], v[232:235], v[180:183], v[80:95]
	ds_read_b64_tr_b16 v[232:233], v3 offset:21184
	ds_read_b64_tr_b16 v[234:235], v3 offset:26432
	s_waitcnt vmcnt(0)
	ds_write_b128 v145, v[4:7]
	ds_write_b128 v145, v[8:11] offset:16
	ds_write_b128 v145, v[12:15] offset:32
	ds_write_b128 v145, v[146:149] offset:48
	ds_write_b128 v145, v[150:153] offset:64
	global_load_dwordx4 v[4:7], v[252:253], off offset:80
	global_load_dwordx4 v[8:11], v[252:253], off offset:96
	global_load_dwordx4 v[12:15], v[252:253], off offset:112
	global_load_dwordx4 v[146:149], v[252:253], off offset:128
	global_load_dwordx4 v[150:153], v[252:253], off offset:144
	s_waitcnt lgkmcnt(15)
	v_mfma_f32_32x32x16_bf16 v[64:79], v[236:239], v[180:183], v[64:79]
	ds_read_b64_tr_b16 v[236:237], v3 offset:21248
	ds_read_b64_tr_b16 v[238:239], v3 offset:26496
	s_waitcnt lgkmcnt(15)
	v_mfma_f32_32x32x16_bf16 v[48:63], v[240:243], v[180:183], v[48:63]
	ds_read_b64_tr_b16 v[240:241], v3 offset:21312
	ds_read_b64_tr_b16 v[242:243], v3 offset:26560
	s_waitcnt lgkmcnt(15)
	v_mfma_f32_32x32x16_bf16 v[32:47], v[244:247], v[180:183], v[32:47]
	ds_read_b64_tr_b16 v[244:245], v3 offset:21376
	ds_read_b64_tr_b16 v[246:247], v3 offset:26624
	s_waitcnt lgkmcnt(15)
	v_mfma_f32_32x32x16_bf16 v[16:31], v[248:251], v[180:183], v[16:31]
	ds_read_b64_tr_b16 v[248:249], v3 offset:21440
	ds_read_b64_tr_b16 v[250:251], v3 offset:26688
	s_waitcnt lgkmcnt(15)
	v_mfma_f32_32x32x16_bf16 v[128:143], v[220:223], v[184:187], v[128:143]
	ds_read_b64_tr_b16 v[220:221], v3 offset:31488
	ds_read_b64_tr_b16 v[222:223], v3 offset:36736
	s_waitcnt lgkmcnt(15)
	v_mfma_f32_32x32x16_bf16 v[112:127], v[224:227], v[184:187], v[112:127]
	ds_read_b64_tr_b16 v[224:225], v3 offset:31552
	ds_read_b64_tr_b16 v[226:227], v3 offset:36800
	s_waitcnt lgkmcnt(15)
	v_mfma_f32_32x32x16_bf16 v[96:111], v[228:231], v[184:187], v[96:111]
	ds_read_b64_tr_b16 v[228:229], v3 offset:31616
	ds_read_b64_tr_b16 v[230:231], v3 offset:36864
	s_waitcnt lgkmcnt(15)
	v_mfma_f32_32x32x16_bf16 v[80:95], v[232:235], v[184:187], v[80:95]
	ds_read_b64_tr_b16 v[232:233], v3 offset:31680
	ds_read_b64_tr_b16 v[234:235], v3 offset:36928
	s_waitcnt lgkmcnt(14)
	v_mfma_f32_32x32x16_bf16 v[64:79], v[236:239], v[184:187], v[64:79]
	ds_read_b64_tr_b16 v[236:237], v3 offset:31744
	ds_read_b64_tr_b16 v[238:239], v3 offset:36992
	s_waitcnt lgkmcnt(14)
	v_mfma_f32_32x32x16_bf16 v[48:63], v[240:243], v[184:187], v[48:63]
	ds_read_b64_tr_b16 v[240:241], v3 offset:31808
	ds_read_b64_tr_b16 v[242:243], v3 offset:37056
	s_waitcnt lgkmcnt(14)
	v_mfma_f32_32x32x16_bf16 v[32:47], v[244:247], v[184:187], v[32:47]
	ds_read_b64_tr_b16 v[244:245], v3 offset:31872
	ds_read_b64_tr_b16 v[246:247], v3 offset:37120
	s_waitcnt lgkmcnt(14)
	v_mfma_f32_32x32x16_bf16 v[16:31], v[248:251], v[184:187], v[16:31]
	ds_read_b64_tr_b16 v[248:249], v3 offset:31936
	ds_read_b64_tr_b16 v[250:251], v3 offset:37184
	s_waitcnt lgkmcnt(14)
	v_mfma_f32_32x32x16_bf16 v[128:143], v[220:223], v[188:191], v[128:143]
	s_waitcnt lgkmcnt(12)
	v_mfma_f32_32x32x16_bf16 v[112:127], v[224:227], v[188:191], v[112:127]
	s_waitcnt lgkmcnt(10)
	v_mfma_f32_32x32x16_bf16 v[96:111], v[228:231], v[188:191], v[96:111]
	s_waitcnt lgkmcnt(8)
	v_mfma_f32_32x32x16_bf16 v[80:95], v[232:235], v[188:191], v[80:95]
	s_waitcnt lgkmcnt(6)
	v_mfma_f32_32x32x16_bf16 v[64:79], v[236:239], v[188:191], v[64:79]
	s_waitcnt lgkmcnt(4)
	v_mfma_f32_32x32x16_bf16 v[48:63], v[240:243], v[188:191], v[48:63]
	s_waitcnt lgkmcnt(2)
	v_mfma_f32_32x32x16_bf16 v[32:47], v[244:247], v[188:191], v[32:47]
	s_waitcnt lgkmcnt(0)
	v_mfma_f32_32x32x16_bf16 v[16:31], v[248:251], v[188:191], v[16:31]
	s_waitcnt vmcnt(0)
	ds_write_b128 v145, v[4:7] offset:80
	ds_write_b128 v145, v[8:11] offset:96
	ds_write_b128 v145, v[12:15] offset:112
	ds_write_b128 v145, v[146:149] offset:128
	ds_write_b128 v145, v[150:153] offset:144
	s_mov_b64 s[8:9], 0xa000
	v_lshl_add_u64 v[252:253], v[252:253], 0, s[8:9]
	s_add_i32 s8, s30, 2
	s_cmp_ge_i32 s8, s27
	s_cbranch_scc1 .Lav_nopf
	global_load_dwordx4 v[4:7], v[252:253], off
	global_load_dwordx4 v[8:11], v[252:253], off offset:16
	global_load_dwordx4 v[12:15], v[252:253], off offset:32
	global_load_dwordx4 v[146:149], v[252:253], off offset:48
	global_load_dwordx4 v[150:153], v[252:253], off offset:64

.Lav_noscale2:
	ds_read_b64_tr_b16 v[240:241], v3 offset:320
	ds_read_b64_tr_b16 v[242:243], v3 offset:5568
	ds_read_b64_tr_b16 v[244:245], v3 offset:384
	ds_read_b64_tr_b16 v[246:247], v3 offset:5632
	ds_read_b64_tr_b16 v[248:249], v3 offset:448
	ds_read_b64_tr_b16 v[250:251], v3 offset:5696
	s_waitcnt lgkmcnt(14)
	v_mfma_f32_32x32x16_bf16 v[128:143], v[220:223], v[176:179], v[128:143]
	ds_read_b64_tr_b16 v[220:221], v3 offset:10496
	ds_read_b64_tr_b16 v[222:223], v3 offset:15744
	s_waitcnt lgkmcnt(14)
	v_mfma_f32_32x32x16_bf16 v[112:127], v[224:227], v[176:179], v[112:127]
	ds_read_b64_tr_b16 v[224:225], v3 offset:10560
	ds_read_b64_tr_b16 v[226:227], v3 offset:15808
	s_waitcnt lgkmcnt(14)
	v_mfma_f32_32x32x16_bf16 v[96:111], v[228:231], v[176:179], v[96:111]
	ds_read_b64_tr_b16 v[228:229], v3 offset:10624
	ds_read_b64_tr_b16 v[230:231], v3 offset:15872
	s_waitcnt lgkmcnt(14)
	v_mfma_f32_32x32x16_bf16 v[80:95], v[232:235], v[176:179], v[80:95]
	ds_read_b64_tr_b16 v[232:233], v3 offset:10688
	ds_read_b64_tr_b16 v[234:235], v3 offset:15936
	s_waitcnt lgkmcnt(14)
	v_mfma_f32_32x32x16_bf16 v[64:79], v[236:239], v[176:179], v[64:79]
	ds_read_b64_tr_b16 v[236:237], v3 offset:10752
	ds_read_b64_tr_b16 v[238:239], v3 offset:16000
	s_waitcnt lgkmcnt(14)
	v_mfma_f32_32x32x16_bf16 v[48:63], v[240:243], v[176:179], v[48:63]
	ds_read_b64_tr_b16 v[240:241], v3 offset:10816
	ds_read_b64_tr_b16 v[242:243], v3 offset:16064
	s_waitcnt lgkmcnt(14)
	v_mfma_f32_32x32x16_bf16 v[32:47], v[244:247], v[176:179], v[32:47]
	ds_read_b64_tr_b16 v[244:245], v3 offset:10880
	ds_read_b64_tr_b16 v[246:247], v3 offset:16128
	s_waitcnt lgkmcnt(14)
	v_mfma_f32_32x32x16_bf16 v[16:31], v[248:251], v[176:179], v[16:31]
	ds_read_b64_tr_b16 v[248:249], v3 offset:10944
	ds_read_b64_tr_b16 v[250:251], v3 offset:16192
	s_waitcnt lgkmcnt(14)
	v_mfma_f32_32x32x16_bf16 v[128:143], v[220:223], v[180:183], v[128:143]
	ds_read_b64_tr_b16 v[220:221], v3 offset:20992
	ds_read_b64_tr_b16 v[222:223], v3 offset:26240
	s_waitcnt lgkmcnt(14)
	v_mfma_f32_32x32x16_bf16 v[112:127], v[224:227], v[180:183], v[112:127]
	ds_read_b64_tr_b16 v[224:225], v3 offset:21056
	ds_read_b64_tr_b16 v[226:227], v3 offset:26304
	s_waitcnt lgkmcnt(14)
	v_mfma_f32_32x32x16_bf16 v[96:111], v[228:231], v[180:183], v[96:111]
	ds_read_b64_tr_b16 v[228:229], v3 offset:21120
	ds_read_b64_tr_b16 v[230:231], v3 offset:26368
	s_waitcnt lgkmcnt(14)
	v_mfma_f32_32x32x16_bf16 v[80:95], v[232:235], v[180:183], v[80:95]
	ds_read_b64_tr_b16 v[232:233], v3 offset:21184
	ds_read_b64_tr_b16 v[234:235], v3 offset:26432
	s_waitcnt lgkmcnt(14)
	v_mfma_f32_32x32x16_bf16 v[64:79], v[236:239], v[180:183], v[64:79]
	ds_read_b64_tr_b16 v[236:237], v3 offset:21248
	ds_read_b64_tr_b16 v[238:239], v3 offset:26496
	s_waitcnt lgkmcnt(14)
	v_mfma_f32_32x32x16_bf16 v[48:63], v[240:243], v[180:183], v[48:63]
	ds_read_b64_tr_b16 v[240:241], v3 offset:21312
	ds_read_b64_tr_b16 v[242:243], v3 offset:26560
	s_waitcnt lgkmcnt(14)
	v_mfma_f32_32x32x16_bf16 v[32:47], v[244:247], v[180:183], v[32:47]
	ds_read_b64_tr_b16 v[244:245], v3 offset:21376
	ds_read_b64_tr_b16 v[246:247], v3 offset:26624
	s_waitcnt lgkmcnt(14)
	v_mfma_f32_32x32x16_bf16 v[16:31], v[248:251], v[180:183], v[16:31]
	ds_read_b64_tr_b16 v[248:249], v3 offset:21440
	ds_read_b64_tr_b16 v[250:251], v3 offset:26688
	s_waitcnt lgkmcnt(14)
	v_mfma_f32_32x32x16_bf16 v[128:143], v[220:223], v[184:187], v[128:143]
	ds_read_b64_tr_b16 v[220:221], v3 offset:31488
	ds_read_b64_tr_b16 v[222:223], v3 offset:36736
	s_waitcnt lgkmcnt(14)
	v_mfma_f32_32x32x16_bf16 v[112:127], v[224:227], v[184:187], v[112:127]
	ds_read_b64_tr_b16 v[224:225], v3 offset:31552
	ds_read_b64_tr_b16 v[226:227], v3 offset:36800
	s_waitcnt lgkmcnt(14)
	v_mfma_f32_32x32x16_bf16 v[96:111], v[228:231], v[184:187], v[96:111]
	ds_read_b64_tr_b16 v[228:229], v3 offset:31616
	ds_read_b64_tr_b16 v[230:231], v3 offset:36864
	s_waitcnt lgkmcnt(14)
	v_mfma_f32_32x32x16_bf16 v[80:95], v[232:235], v[184:187], v[80:95]
	ds_read_b64_tr_b16 v[232:233], v3 offset:31680
	ds_read_b64_tr_b16 v[234:235], v3 offset:36928
	s_waitcnt lgkmcnt(14)
	v_mfma_f32_32x32x16_bf16 v[64:79], v[236:239], v[184:187], v[64:79]
	ds_read_b64_tr_b16 v[236:237], v3 offset:31744
	ds_read_b64_tr_b16 v[238:239], v3 offset:36992
	s_waitcnt lgkmcnt(14)
	v_mfma_f32_32x32x16_bf16 v[48:63], v[240:243], v[184:187], v[48:63]
	ds_read_b64_tr_b16 v[240:241], v3 offset:31808
	ds_read_b64_tr_b16 v[242:243], v3 offset:37056
	s_waitcnt lgkmcnt(14)
	v_mfma_f32_32x32x16_bf16 v[32:47], v[244:247], v[184:187], v[32:47]
	ds_read_b64_tr_b16 v[244:245], v3 offset:31872
	ds_read_b64_tr_b16 v[246:247], v3 offset:37120
	s_waitcnt lgkmcnt(14)
	v_mfma_f32_32x32x16_bf16 v[16:31], v[248:251], v[184:187], v[16:31]
	ds_read_b64_tr_b16 v[248:249], v3 offset:31936
	ds_read_b64_tr_b16 v[250:251], v3 offset:37184
	s_waitcnt lgkmcnt(14)
	v_mfma_f32_32x32x16_bf16 v[128:143], v[220:223], v[188:191], v[128:143]
	s_waitcnt lgkmcnt(12)
	v_mfma_f32_32x32x16_bf16 v[112:127], v[224:227], v[188:191], v[112:127]
	s_waitcnt lgkmcnt(10)
	v_mfma_f32_32x32x16_bf16 v[96:111], v[228:231], v[188:191], v[96:111]
	s_waitcnt lgkmcnt(8)
	v_mfma_f32_32x32x16_bf16 v[80:95], v[232:235], v[188:191], v[80:95]
	s_waitcnt lgkmcnt(6)
	v_mfma_f32_32x32x16_bf16 v[64:79], v[236:239], v[188:191], v[64:79]
	s_waitcnt lgkmcnt(4)
	v_mfma_f32_32x32x16_bf16 v[48:63], v[240:243], v[188:191], v[48:63]
	s_waitcnt lgkmcnt(2)
	v_mfma_f32_32x32x16_bf16 v[32:47], v[244:247], v[188:191], v[32:47]
	s_waitcnt lgkmcnt(0)
	v_mfma_f32_32x32x16_bf16 v[16:31], v[248:251], v[188:191], v[16:31]
	s_waitcnt lgkmcnt(0)
	s_branch .LBB0_401
.Lav_stage0:
	s_cmp_lt_i32 s27, 2
	s_cbranch_scc1 .Lav_s0done
	s_add_i32 s8, s19, 2
	s_mul_hi_u32 s9, s8, 0xaaaaaaab
	s_lshr_b32 s9, s9, 1
	s_mul_i32 s9, s9, 3
	s_sub_i32 s8, s8, s9
	s_mul_i32 s8, s8, 0xa400
	v_add_u32_e32 v145, s8, v170
	global_load_dwordx4 v[4:7], v[252:253], off
	global_load_dwordx4 v[8:11], v[252:253], off offset:16
	global_load_dwordx4 v[12:15], v[252:253], off offset:32
	global_load_dwordx4 v[146:149], v[252:253], off offset:48
	global_load_dwordx4 v[150:153], v[252:253], off offset:64
	global_load_dwordx4 v[220:223], v[252:253], off offset:80
	global_load_dwordx4 v[224:227], v[252:253], off offset:96
	global_load_dwordx4 v[228:231], v[252:253], off offset:112
	global_load_dwordx4 v[232:235], v[252:253], off offset:128
	global_load_dwordx4 v[236:239], v[252:253], off offset:144
	s_waitcnt vmcnt(0)
	ds_write_b128 v145, v[4:7]
	ds_write_b128 v145, v[8:11] offset:16
	ds_write_b128 v145, v[12:15] offset:32
	ds_write_b128 v145, v[146:149] offset:48
	ds_write_b128 v145, v[150:153] offset:64
	ds_write_b128 v145, v[220:223] offset:80
	ds_write_b128 v145, v[224:227] offset:96
	ds_write_b128 v145, v[228:231] offset:112
	ds_write_b128 v145, v[232:235] offset:128
	ds_write_b128 v145, v[236:239] offset:144
	s_mov_b64 s[8:9], 0xa000
	v_lshl_add_u64 v[252:253], v[252:253], 0, s[8:9]
	s_cmp_lt_i32 s27, 3
	s_cbranch_scc1 .Lav_s0done
	global_load_dwordx4 v[4:7], v[252:253], off
	global_load_dwordx4 v[8:11], v[252:253], off offset:16
	global_load_dwordx4 v[12:15], v[252:253], off offset:32
	global_load_dwordx4 v[146:149], v[252:253], off offset:48
	global_load_dwordx4 v[150:153], v[252:253], off offset:64
.Lav_s0done:
	s_waitcnt lgkmcnt(0)
.LBB0_401:
	s_add_i32 s8, s30, 1
	s_add_i32 s18, s18, 4
	s_add_i32 s19, s19, 1
	s_cmp_eq_u32 s30, s27
	v_add_u32_e32 v144, 0xa400, v144
	s_barrier
	s_cbranch_scc1 .LBB0_404
	s_mov_b32 s30, s8
	s_cmp_eq_u32 s30, 0
	s_cbranch_scc0 .LBB0_397
	s_branch .LBB0_401
